# code placement: recurrence steps a whole number of 8-byte units, every 8-byte instruction 8-byte aligned (8-byte SALU fillers, v_add e64)
# speedup vs baseline: 1.0131x; 1.0021x over previous
.LBB0_679:
	s_lshl_b32 s6, s25, 2
	s_and_b32 s6, s6, 28
	s_ashr_i32 s7, s25, 6
	v_readlane_b32 s8, v253, 44
	s_add_i32 s6, s6, s7
	v_readlane_b32 s9, v253, 45
	s_ashr_i32 s26, s6, 3
	s_and_b32 s27, s6, 7
	s_mov_b64 s[6:7], -1
	s_and_b64 vcc, exec, s[8:9]
	s_cbranch_vccz .LBB0_694
	s_and_b32 s6, s25, 56
	v_add_u32_e32 v46, s6, v57
	s_lshr_b32 s6, s25, 6
	s_and_b32 s7, s24, 4
	s_add_i32 s7, s7, s6
	s_and_b32 s6, s7, 7
	s_mul_i32 s29, s26, 0x808000
	s_lshl_b32 s6, s6, 8
	s_mul_hi_i32 s28, s26, 0x808000
	s_or_b32 s6, s29, s6
	v_ashrrev_i32_e32 v47, 31, v46
	s_waitcnt lgkmcnt(0)
	s_barrier
	v_mov_b32_e32 v0, s6
	v_mov_b32_e32 v1, s28
	v_lshl_add_u64 v[0:1], v[46:47], 2, v[0:1]
	v_mov_b32_e32 v162, v163
	v_lshlrev_b32_e32 v86, 2, v46
	v_lshl_add_u64 v[48:49], v[44:45], 0, v[0:1]
	v_lshl_add_u64 v[50:51], s[90:91], 0, v[0:1]
	s_mov_b32 s30, 0
	s_mov_b64 s[88:89], 0
	s_movk_i32 s31, 0x1010
	v_mov_b64_e32 v[52:53], v[162:163]
	v_lshrrev_b32_e32 v2, 1, v57
	v_and_b32_e32 v3, 1, v57
	v_mul_u32_u24_e32 v2, 0x1200, v2
	v_lshl_add_u32 v2, v3, 6, v2
	v_add_u32_e32 v2, 0x1c000, v2
	v_mbcnt_lo_u32_b32 v3, -1, 0
	v_mbcnt_hi_u32_b32 v3, -1, v3
	v_and_b32_e32 v87, 31, v3
	v_lshrrev_b32_e32 v3, 1, v87
	v_lshl_add_u32 v91, v3, 2, v2
	v_mul_u32_u24_e32 v3, 0x90, v87
	v_add_u32_e32 v92, v3, v2
	v_lshlrev_b32_e32 v94, 11, v87
	v_mov_b32_e32 v95, 0
	s_nop 0
	s_branch .LBB0_682

.LBB0_682:
	s_bitcmp1_b32 s30, 0
	s_cselect_b32 s6, 0xe000, 0
	s_add_i32 s6, s6, 0
	v_add_u32_e32 v90, s6, v58
	v_sub_u32_e32 v88, v90, v61
	v_add_u32_e32 v89, s6, v86
	ds_read_b128 v[4:7], v90 offset:0x4000
	ds_read_b128 v[8:11], v90 offset:0x0
	ds_read2st64_b32 v[108:109], v89 offset0:192 offset1:193
	ds_read2st64_b64 v[100:103], v88 offset0:64 offset1:65
	ds_read_b128 v[112:115], v90 offset:0x4200
	ds_read_b128 v[96:99], v90 offset:0x200
	ds_read_b128 v[120:123], v90 offset:0x4400
	ds_read_b128 v[124:127], v90 offset:0x400
	v_mov_b32_e32 v93, v91
	s_waitcnt lgkmcnt(5)
	v_pk_mul_f32 v[0:1], v[52:53], v[4:5] op_sel_hi:[0,1]
	v_pk_fma_f32 v[0:1], v[52:53], v[6:7], v[0:1] op_sel:[1,0,0]
	v_pk_mul_f32 v[10:11], v[108:109], v[10:11] op_sel_hi:[0,1]
	v_pk_fma_f32 v[54:55], v[52:53], v[8:9], v[10:11]
	v_add_f32_dpp v0, v0, v0 quad_perm:[1,0,3,2] row_mask:0xf bank_mask:0xf bound_ctrl:1
	v_add_f32_dpp v1, v1, v1 quad_perm:[1,0,3,2] row_mask:0xf bank_mask:0xf bound_ctrl:1
	s_mov_b32 s6, 0x12345
	ds_read_b128 v[4:7], v90 offset:0x4600
	v_add_f32_dpp v0, v0, v0 quad_perm:[2,3,0,1] row_mask:0xf bank_mask:0xf bound_ctrl:1
	s_mov_b32 s6, 0x12345
	ds_read_b128 v[8:11], v90 offset:0x600
	v_add_f32_dpp v0, v0, v0 row_half_mirror row_mask:0xf bank_mask:0xf bound_ctrl:1
	s_mov_b32 s6, 0x12345
	ds_read2st64_b32 v[110:111], v89 offset0:194 offset1:195
	ds_read2st64_b64 v[104:107], v88 offset0:66 offset1:67
	v_add_f32_dpp v2, v0, v0 row_mirror row_mask:0xf bank_mask:0xf bound_ctrl:1
	v_add_f32_dpp v0, v0, v0 row_mirror row_mask:0xf bank_mask:0xf bound_ctrl:1
	s_mov_b32 s6, 0x12345
	s_waitcnt lgkmcnt(6)
	v_permlane16_swap_b32_e32 v0, v2
	v_add_f32_e64 v0, v0, v2
	v_pk_fma_f32 v[52:53], v[100:101], v[0:1], v[54:55] op_sel_hi:[1,0,1]
	v_pk_mul_f32 v[118:119], v[52:53], v[112:113] op_sel_hi:[0,1]
	v_pk_fma_f32 v[118:119], v[52:53], v[114:115], v[118:119] op_sel:[1,0,0]
	v_pk_mul_f32 v[98:99], v[108:109], v[98:99] op_sel:[1,0]
	v_pk_fma_f32 v[54:55], v[52:53], v[96:97], v[98:99]
	v_add_f32_dpp v118, v118, v118 quad_perm:[1,0,3,2] row_mask:0xf bank_mask:0xf bound_ctrl:1
	v_add_f32_dpp v119, v119, v119 quad_perm:[1,0,3,2] row_mask:0xf bank_mask:0xf bound_ctrl:1
	s_mov_b32 s6, 0x12345
	ds_read_b128 v[112:115], v90 offset:0x4800
	v_add_f32_dpp v118, v118, v118 quad_perm:[2,3,0,1] row_mask:0xf bank_mask:0xf bound_ctrl:1
	s_mov_b32 s6, 0x12345
	ds_read_b128 v[96:99], v90 offset:0x800
	v_add_f32_dpp v118, v118, v118 row_half_mirror row_mask:0xf bank_mask:0xf bound_ctrl:1
	s_mov_b32 s6, 0x12345
	ds_write2_b32 v93, v1, v119 offset0:0 offset1:36
	v_add_f32_dpp v2, v118, v118 row_mirror row_mask:0xf bank_mask:0xf bound_ctrl:1
	v_add_f32_dpp v118, v118, v118 row_mirror row_mask:0xf bank_mask:0xf bound_ctrl:1
	s_mov_b32 s6, 0x12345
	s_waitcnt lgkmcnt(4)
	v_permlane16_swap_b32_e32 v118, v2
	v_add_f32_e64 v118, v118, v2
	v_pk_fma_f32 v[52:53], v[102:103], v[118:119], v[54:55] op_sel_hi:[1,0,1]
	v_pk_mul_f32 v[0:1], v[52:53], v[120:121] op_sel_hi:[0,1]
	v_pk_fma_f32 v[0:1], v[52:53], v[122:123], v[0:1] op_sel:[1,0,0]
	v_pk_mul_f32 v[126:127], v[110:111], v[126:127] op_sel_hi:[0,1]
	v_pk_fma_f32 v[54:55], v[52:53], v[124:125], v[126:127]
	v_add_f32_dpp v0, v0, v0 quad_perm:[1,0,3,2] row_mask:0xf bank_mask:0xf bound_ctrl:1
	v_add_f32_dpp v1, v1, v1 quad_perm:[1,0,3,2] row_mask:0xf bank_mask:0xf bound_ctrl:1
	s_mov_b32 s6, 0x12345
	ds_read_b128 v[120:123], v90 offset:0x4a00
	v_add_f32_dpp v0, v0, v0 quad_perm:[2,3,0,1] row_mask:0xf bank_mask:0xf bound_ctrl:1
	s_mov_b32 s6, 0x12345
	ds_read_b128 v[124:127], v90 offset:0xa00
	v_add_f32_dpp v0, v0, v0 row_half_mirror row_mask:0xf bank_mask:0xf bound_ctrl:1
	s_mov_b32 s6, 0x12345
	ds_read2st64_b32 v[108:109], v89 offset0:196 offset1:197
	ds_read2st64_b64 v[100:103], v88 offset0:68 offset1:69
	v_add_f32_dpp v2, v0, v0 row_mirror row_mask:0xf bank_mask:0xf bound_ctrl:1
	v_add_f32_dpp v0, v0, v0 row_mirror row_mask:0xf bank_mask:0xf bound_ctrl:1
	s_mov_b32 s6, 0x12345
	s_waitcnt lgkmcnt(7)
	v_permlane16_swap_b32_e32 v0, v2
	v_add_f32_e64 v0, v0, v2
	v_pk_fma_f32 v[52:53], v[104:105], v[0:1], v[54:55] op_sel_hi:[1,0,1]
	v_pk_mul_f32 v[118:119], v[52:53], v[4:5] op_sel_hi:[0,1]
	v_pk_fma_f32 v[118:119], v[52:53], v[6:7], v[118:119] op_sel:[1,0,0]
	v_pk_mul_f32 v[10:11], v[110:111], v[10:11] op_sel:[1,0]
	v_pk_fma_f32 v[54:55], v[52:53], v[8:9], v[10:11]
	v_add_f32_dpp v118, v118, v118 quad_perm:[1,0,3,2] row_mask:0xf bank_mask:0xf bound_ctrl:1
	v_add_f32_dpp v119, v119, v119 quad_perm:[1,0,3,2] row_mask:0xf bank_mask:0xf bound_ctrl:1
	s_mov_b32 s6, 0x12345
	ds_read_b128 v[4:7], v90 offset:0x4c00
	v_add_f32_dpp v118, v118, v118 quad_perm:[2,3,0,1] row_mask:0xf bank_mask:0xf bound_ctrl:1
	s_mov_b32 s6, 0x12345
	ds_read_b128 v[8:11], v90 offset:0xc00
	v_add_f32_dpp v118, v118, v118 row_half_mirror row_mask:0xf bank_mask:0xf bound_ctrl:1
	s_mov_b32 s6, 0x12345
	ds_write2_b32 v93, v1, v119 offset0:72 offset1:108
	v_add_f32_dpp v2, v118, v118 row_mirror row_mask:0xf bank_mask:0xf bound_ctrl:1
	v_add_f32_dpp v118, v118, v118 row_mirror row_mask:0xf bank_mask:0xf bound_ctrl:1
	s_mov_b32 s6, 0x12345
	s_waitcnt lgkmcnt(4)
	v_permlane16_swap_b32_e32 v118, v2
	v_add_f32_e64 v118, v118, v2
	v_pk_fma_f32 v[52:53], v[106:107], v[118:119], v[54:55] op_sel_hi:[1,0,1]
	v_pk_mul_f32 v[0:1], v[52:53], v[112:113] op_sel_hi:[0,1]
	v_pk_fma_f32 v[0:1], v[52:53], v[114:115], v[0:1] op_sel:[1,0,0]
	v_pk_mul_f32 v[98:99], v[108:109], v[98:99] op_sel_hi:[0,1]
	v_pk_fma_f32 v[54:55], v[52:53], v[96:97], v[98:99]
	v_add_f32_dpp v0, v0, v0 quad_perm:[1,0,3,2] row_mask:0xf bank_mask:0xf bound_ctrl:1
	v_add_f32_dpp v1, v1, v1 quad_perm:[1,0,3,2] row_mask:0xf bank_mask:0xf bound_ctrl:1
	s_mov_b32 s6, 0x12345
	ds_read_b128 v[112:115], v90 offset:0x4e00
	v_add_f32_dpp v0, v0, v0 quad_perm:[2,3,0,1] row_mask:0xf bank_mask:0xf bound_ctrl:1
	s_mov_b32 s6, 0x12345
	ds_read_b128 v[96:99], v90 offset:0xe00
	v_add_f32_dpp v0, v0, v0 row_half_mirror row_mask:0xf bank_mask:0xf bound_ctrl:1
	s_mov_b32 s6, 0x12345
	ds_read2st64_b32 v[110:111], v89 offset0:198 offset1:199
	ds_read2st64_b64 v[104:107], v88 offset0:70 offset1:71
	v_add_f32_dpp v2, v0, v0 row_mirror row_mask:0xf bank_mask:0xf bound_ctrl:1
	v_add_f32_dpp v0, v0, v0 row_mirror row_mask:0xf bank_mask:0xf bound_ctrl:1
	s_mov_b32 s6, 0x12345
	s_waitcnt lgkmcnt(7)
	v_permlane16_swap_b32_e32 v0, v2
	v_add_f32_e64 v0, v0, v2
	v_pk_fma_f32 v[52:53], v[100:101], v[0:1], v[54:55] op_sel_hi:[1,0,1]
	v_pk_mul_f32 v[118:119], v[52:53], v[120:121] op_sel_hi:[0,1]
	v_pk_fma_f32 v[118:119], v[52:53], v[122:123], v[118:119] op_sel:[1,0,0]
	v_pk_mul_f32 v[126:127], v[108:109], v[126:127] op_sel:[1,0]
	v_pk_fma_f32 v[54:55], v[52:53], v[124:125], v[126:127]
	v_add_f32_dpp v118, v118, v118 quad_perm:[1,0,3,2] row_mask:0xf bank_mask:0xf bound_ctrl:1
	v_add_f32_dpp v119, v119, v119 quad_perm:[1,0,3,2] row_mask:0xf bank_mask:0xf bound_ctrl:1
	s_mov_b32 s6, 0x12345
	ds_read_b128 v[120:123], v90 offset:0x5000
	v_add_f32_dpp v118, v118, v118 quad_perm:[2,3,0,1] row_mask:0xf bank_mask:0xf bound_ctrl:1
	s_mov_b32 s6, 0x12345
	ds_read_b128 v[124:127], v90 offset:0x1000
	v_add_f32_dpp v118, v118, v118 row_half_mirror row_mask:0xf bank_mask:0xf bound_ctrl:1
	s_mov_b32 s6, 0x12345
	ds_write2_b32 v93, v1, v119 offset0:144 offset1:180
	v_add_f32_dpp v2, v118, v118 row_mirror row_mask:0xf bank_mask:0xf bound_ctrl:1
	v_add_f32_dpp v118, v118, v118 row_mirror row_mask:0xf bank_mask:0xf bound_ctrl:1
	s_mov_b32 s6, 0x12345
	s_waitcnt lgkmcnt(4)
	v_permlane16_swap_b32_e32 v118, v2
	v_add_f32_e64 v118, v118, v2
	v_pk_fma_f32 v[52:53], v[102:103], v[118:119], v[54:55] op_sel_hi:[1,0,1]
	v_pk_mul_f32 v[0:1], v[52:53], v[4:5] op_sel_hi:[0,1]
	v_pk_fma_f32 v[0:1], v[52:53], v[6:7], v[0:1] op_sel:[1,0,0]
	v_pk_mul_f32 v[10:11], v[110:111], v[10:11] op_sel_hi:[0,1]
	v_pk_fma_f32 v[54:55], v[52:53], v[8:9], v[10:11]
	v_add_f32_dpp v0, v0, v0 quad_perm:[1,0,3,2] row_mask:0xf bank_mask:0xf bound_ctrl:1
	v_add_f32_dpp v1, v1, v1 quad_perm:[1,0,3,2] row_mask:0xf bank_mask:0xf bound_ctrl:1
	s_mov_b32 s6, 0x12345
	ds_read_b128 v[4:7], v90 offset:0x5200
	v_add_f32_dpp v0, v0, v0 quad_perm:[2,3,0,1] row_mask:0xf bank_mask:0xf bound_ctrl:1
	s_mov_b32 s6, 0x12345
	ds_read_b128 v[8:11], v90 offset:0x1200
	v_add_f32_dpp v0, v0, v0 row_half_mirror row_mask:0xf bank_mask:0xf bound_ctrl:1
	s_mov_b32 s6, 0x12345
	ds_read2st64_b32 v[108:109], v89 offset0:200 offset1:201
	ds_read2st64_b64 v[100:103], v88 offset0:72 offset1:73
	v_add_f32_dpp v2, v0, v0 row_mirror row_mask:0xf bank_mask:0xf bound_ctrl:1
	v_add_f32_dpp v0, v0, v0 row_mirror row_mask:0xf bank_mask:0xf bound_ctrl:1
	s_mov_b32 s6, 0x12345
	s_waitcnt lgkmcnt(7)
	v_permlane16_swap_b32_e32 v0, v2
	v_add_f32_e64 v0, v0, v2
	v_pk_fma_f32 v[52:53], v[104:105], v[0:1], v[54:55] op_sel_hi:[1,0,1]
	v_pk_mul_f32 v[118:119], v[52:53], v[112:113] op_sel_hi:[0,1]
	v_pk_fma_f32 v[118:119], v[52:53], v[114:115], v[118:119] op_sel:[1,0,0]
	v_pk_mul_f32 v[98:99], v[110:111], v[98:99] op_sel:[1,0]
	v_pk_fma_f32 v[54:55], v[52:53], v[96:97], v[98:99]
	v_add_f32_dpp v118, v118, v118 quad_perm:[1,0,3,2] row_mask:0xf bank_mask:0xf bound_ctrl:1
	v_add_f32_dpp v119, v119, v119 quad_perm:[1,0,3,2] row_mask:0xf bank_mask:0xf bound_ctrl:1
	s_mov_b32 s6, 0x12345
	ds_read_b128 v[112:115], v90 offset:0x5400
	v_add_f32_dpp v118, v118, v118 quad_perm:[2,3,0,1] row_mask:0xf bank_mask:0xf bound_ctrl:1
	s_mov_b32 s6, 0x12345
	ds_read_b128 v[96:99], v90 offset:0x1400
	v_add_f32_dpp v118, v118, v118 row_half_mirror row_mask:0xf bank_mask:0xf bound_ctrl:1
	s_mov_b32 s6, 0x12345
	ds_write2_b32 v93, v1, v119 offset0:216 offset1:252
	v_add_f32_dpp v2, v118, v118 row_mirror row_mask:0xf bank_mask:0xf bound_ctrl:1
	v_add_f32_dpp v118, v118, v118 row_mirror row_mask:0xf bank_mask:0xf bound_ctrl:1
	s_mov_b32 s6, 0x12345
	s_waitcnt lgkmcnt(4)
	v_permlane16_swap_b32_e32 v118, v2
	v_add_f32_e64 v118, v118, v2
	v_pk_fma_f32 v[52:53], v[106:107], v[118:119], v[54:55] op_sel_hi:[1,0,1]
	v_pk_mul_f32 v[0:1], v[52:53], v[120:121] op_sel_hi:[0,1]
	v_pk_fma_f32 v[0:1], v[52:53], v[122:123], v[0:1] op_sel:[1,0,0]
	v_pk_mul_f32 v[126:127], v[108:109], v[126:127] op_sel_hi:[0,1]
	v_pk_fma_f32 v[54:55], v[52:53], v[124:125], v[126:127]
	v_add_f32_dpp v0, v0, v0 quad_perm:[1,0,3,2] row_mask:0xf bank_mask:0xf bound_ctrl:1
	v_add_f32_dpp v1, v1, v1 quad_perm:[1,0,3,2] row_mask:0xf bank_mask:0xf bound_ctrl:1
	s_mov_b32 s6, 0x12345
	ds_read_b128 v[120:123], v90 offset:0x5600
	v_add_f32_dpp v0, v0, v0 quad_perm:[2,3,0,1] row_mask:0xf bank_mask:0xf bound_ctrl:1
	s_mov_b32 s6, 0x12345
	ds_read_b128 v[124:127], v90 offset:0x1600
	v_add_f32_dpp v0, v0, v0 row_half_mirror row_mask:0xf bank_mask:0xf bound_ctrl:1
	s_mov_b32 s6, 0x12345
	ds_read2st64_b32 v[110:111], v89 offset0:202 offset1:203
	ds_read2st64_b64 v[104:107], v88 offset0:74 offset1:75
	v_add_f32_dpp v2, v0, v0 row_mirror row_mask:0xf bank_mask:0xf bound_ctrl:1
	v_add_f32_dpp v0, v0, v0 row_mirror row_mask:0xf bank_mask:0xf bound_ctrl:1
	v_add_u32_e32 v93, 0x480, v93
	s_waitcnt lgkmcnt(7)
	v_permlane16_swap_b32_e32 v0, v2
	v_add_f32_e64 v0, v0, v2
	v_pk_fma_f32 v[52:53], v[100:101], v[0:1], v[54:55] op_sel_hi:[1,0,1]
	v_pk_mul_f32 v[118:119], v[52:53], v[4:5] op_sel_hi:[0,1]
	v_pk_fma_f32 v[118:119], v[52:53], v[6:7], v[118:119] op_sel:[1,0,0]
	v_pk_mul_f32 v[10:11], v[108:109], v[10:11] op_sel:[1,0]
	v_pk_fma_f32 v[54:55], v[52:53], v[8:9], v[10:11]
	v_add_f32_dpp v118, v118, v118 quad_perm:[1,0,3,2] row_mask:0xf bank_mask:0xf bound_ctrl:1
	v_add_f32_dpp v119, v119, v119 quad_perm:[1,0,3,2] row_mask:0xf bank_mask:0xf bound_ctrl:1
	s_mov_b32 s6, 0x12345
	ds_read_b128 v[4:7], v90 offset:0x5800
	v_add_f32_dpp v118, v118, v118 quad_perm:[2,3,0,1] row_mask:0xf bank_mask:0xf bound_ctrl:1
	s_mov_b32 s6, 0x12345
	ds_read_b128 v[8:11], v90 offset:0x1800
	v_add_f32_dpp v118, v118, v118 row_half_mirror row_mask:0xf bank_mask:0xf bound_ctrl:1
	s_mov_b32 s6, 0x12345
	ds_write2_b32 v93, v1, v119 offset0:0 offset1:36
	v_add_f32_dpp v2, v118, v118 row_mirror row_mask:0xf bank_mask:0xf bound_ctrl:1
	v_add_f32_dpp v118, v118, v118 row_mirror row_mask:0xf bank_mask:0xf bound_ctrl:1
	s_mov_b32 s6, 0x12345
	s_waitcnt lgkmcnt(4)
	v_permlane16_swap_b32_e32 v118, v2
	v_add_f32_e64 v118, v118, v2
	v_pk_fma_f32 v[52:53], v[102:103], v[118:119], v[54:55] op_sel_hi:[1,0,1]
	v_pk_mul_f32 v[0:1], v[52:53], v[112:113] op_sel_hi:[0,1]
	v_pk_fma_f32 v[0:1], v[52:53], v[114:115], v[0:1] op_sel:[1,0,0]
	v_pk_mul_f32 v[98:99], v[110:111], v[98:99] op_sel_hi:[0,1]
	v_pk_fma_f32 v[54:55], v[52:53], v[96:97], v[98:99]
	v_add_f32_dpp v0, v0, v0 quad_perm:[1,0,3,2] row_mask:0xf bank_mask:0xf bound_ctrl:1
	v_add_f32_dpp v1, v1, v1 quad_perm:[1,0,3,2] row_mask:0xf bank_mask:0xf bound_ctrl:1
	s_mov_b32 s6, 0x12345
	ds_read_b128 v[112:115], v90 offset:0x5a00
	v_add_f32_dpp v0, v0, v0 quad_perm:[2,3,0,1] row_mask:0xf bank_mask:0xf bound_ctrl:1
	s_mov_b32 s6, 0x12345
	ds_read_b128 v[96:99], v90 offset:0x1a00
	v_add_f32_dpp v0, v0, v0 row_half_mirror row_mask:0xf bank_mask:0xf bound_ctrl:1
	s_mov_b32 s6, 0x12345
	ds_read2st64_b32 v[108:109], v89 offset0:204 offset1:205
	ds_read2st64_b64 v[100:103], v88 offset0:76 offset1:77
	v_add_f32_dpp v2, v0, v0 row_mirror row_mask:0xf bank_mask:0xf bound_ctrl:1
	v_add_f32_dpp v0, v0, v0 row_mirror row_mask:0xf bank_mask:0xf bound_ctrl:1
	s_mov_b32 s6, 0x12345
	s_waitcnt lgkmcnt(7)
	v_permlane16_swap_b32_e32 v0, v2
	v_add_f32_e64 v0, v0, v2
	v_pk_fma_f32 v[52:53], v[104:105], v[0:1], v[54:55] op_sel_hi:[1,0,1]
	v_pk_mul_f32 v[118:119], v[52:53], v[120:121] op_sel_hi:[0,1]
	v_pk_fma_f32 v[118:119], v[52:53], v[122:123], v[118:119] op_sel:[1,0,0]
	v_pk_mul_f32 v[126:127], v[110:111], v[126:127] op_sel:[1,0]
	v_pk_fma_f32 v[54:55], v[52:53], v[124:125], v[126:127]
	v_add_f32_dpp v118, v118, v118 quad_perm:[1,0,3,2] row_mask:0xf bank_mask:0xf bound_ctrl:1
	v_add_f32_dpp v119, v119, v119 quad_perm:[1,0,3,2] row_mask:0xf bank_mask:0xf bound_ctrl:1
	s_mov_b32 s6, 0x12345
	ds_read_b128 v[120:123], v90 offset:0x5c00
	v_add_f32_dpp v118, v118, v118 quad_perm:[2,3,0,1] row_mask:0xf bank_mask:0xf bound_ctrl:1
	s_mov_b32 s6, 0x12345
	ds_read_b128 v[124:127], v90 offset:0x1c00
	v_add_f32_dpp v118, v118, v118 row_half_mirror row_mask:0xf bank_mask:0xf bound_ctrl:1
	s_mov_b32 s6, 0x12345
	ds_write2_b32 v93, v1, v119 offset0:72 offset1:108
	v_add_f32_dpp v2, v118, v118 row_mirror row_mask:0xf bank_mask:0xf bound_ctrl:1
	v_add_f32_dpp v118, v118, v118 row_mirror row_mask:0xf bank_mask:0xf bound_ctrl:1
	s_mov_b32 s6, 0x12345
	s_waitcnt lgkmcnt(4)
	v_permlane16_swap_b32_e32 v118, v2
	v_add_f32_e64 v118, v118, v2
	v_pk_fma_f32 v[52:53], v[106:107], v[118:119], v[54:55] op_sel_hi:[1,0,1]
	v_pk_mul_f32 v[0:1], v[52:53], v[4:5] op_sel_hi:[0,1]
	v_pk_fma_f32 v[0:1], v[52:53], v[6:7], v[0:1] op_sel:[1,0,0]
	v_pk_mul_f32 v[10:11], v[108:109], v[10:11] op_sel_hi:[0,1]
	v_pk_fma_f32 v[54:55], v[52:53], v[8:9], v[10:11]
	v_add_f32_dpp v0, v0, v0 quad_perm:[1,0,3,2] row_mask:0xf bank_mask:0xf bound_ctrl:1
	v_add_f32_dpp v1, v1, v1 quad_perm:[1,0,3,2] row_mask:0xf bank_mask:0xf bound_ctrl:1
	s_mov_b32 s6, 0x12345
	ds_read_b128 v[4:7], v90 offset:0x5e00
	v_add_f32_dpp v0, v0, v0 quad_perm:[2,3,0,1] row_mask:0xf bank_mask:0xf bound_ctrl:1
	s_mov_b32 s6, 0x12345
	ds_read_b128 v[8:11], v90 offset:0x1e00
	v_add_f32_dpp v0, v0, v0 row_half_mirror row_mask:0xf bank_mask:0xf bound_ctrl:1
	s_mov_b32 s6, 0x12345
	ds_read2st64_b32 v[110:111], v89 offset0:206 offset1:207
	ds_read2st64_b64 v[104:107], v88 offset0:78 offset1:79
	v_add_f32_dpp v2, v0, v0 row_mirror row_mask:0xf bank_mask:0xf bound_ctrl:1
	v_add_f32_dpp v0, v0, v0 row_mirror row_mask:0xf bank_mask:0xf bound_ctrl:1
	s_mov_b32 s6, 0x12345
	s_waitcnt lgkmcnt(7)
	v_permlane16_swap_b32_e32 v0, v2
	v_add_f32_e64 v0, v0, v2
	v_pk_fma_f32 v[52:53], v[100:101], v[0:1], v[54:55] op_sel_hi:[1,0,1]
	v_pk_mul_f32 v[118:119], v[52:53], v[112:113] op_sel_hi:[0,1]
	v_pk_fma_f32 v[118:119], v[52:53], v[114:115], v[118:119] op_sel:[1,0,0]
	v_pk_mul_f32 v[98:99], v[108:109], v[98:99] op_sel:[1,0]
	v_pk_fma_f32 v[54:55], v[52:53], v[96:97], v[98:99]
	v_add_f32_dpp v118, v118, v118 quad_perm:[1,0,3,2] row_mask:0xf bank_mask:0xf bound_ctrl:1
	v_add_f32_dpp v119, v119, v119 quad_perm:[1,0,3,2] row_mask:0xf bank_mask:0xf bound_ctrl:1
	s_mov_b32 s6, 0x12345
	ds_read_b128 v[112:115], v90 offset:0x6000
	v_add_f32_dpp v118, v118, v118 quad_perm:[2,3,0,1] row_mask:0xf bank_mask:0xf bound_ctrl:1
	s_mov_b32 s6, 0x12345
	ds_read_b128 v[96:99], v90 offset:0x2000
	v_add_f32_dpp v118, v118, v118 row_half_mirror row_mask:0xf bank_mask:0xf bound_ctrl:1
	s_mov_b32 s6, 0x12345
	ds_write2_b32 v93, v1, v119 offset0:144 offset1:180
	v_add_f32_dpp v2, v118, v118 row_mirror row_mask:0xf bank_mask:0xf bound_ctrl:1
	v_add_f32_dpp v118, v118, v118 row_mirror row_mask:0xf bank_mask:0xf bound_ctrl:1
	s_mov_b32 s6, 0x12345
	s_waitcnt lgkmcnt(4)
	v_permlane16_swap_b32_e32 v118, v2
	v_add_f32_e64 v118, v118, v2
	v_pk_fma_f32 v[52:53], v[102:103], v[118:119], v[54:55] op_sel_hi:[1,0,1]
	v_pk_mul_f32 v[0:1], v[52:53], v[120:121] op_sel_hi:[0,1]
	v_pk_fma_f32 v[0:1], v[52:53], v[122:123], v[0:1] op_sel:[1,0,0]
	v_pk_mul_f32 v[126:127], v[110:111], v[126:127] op_sel_hi:[0,1]
	v_pk_fma_f32 v[54:55], v[52:53], v[124:125], v[126:127]
	v_add_f32_dpp v0, v0, v0 quad_perm:[1,0,3,2] row_mask:0xf bank_mask:0xf bound_ctrl:1
	v_add_f32_dpp v1, v1, v1 quad_perm:[1,0,3,2] row_mask:0xf bank_mask:0xf bound_ctrl:1
	s_mov_b32 s6, 0x12345
	ds_read_b128 v[120:123], v90 offset:0x6200
	v_add_f32_dpp v0, v0, v0 quad_perm:[2,3,0,1] row_mask:0xf bank_mask:0xf bound_ctrl:1
	s_mov_b32 s6, 0x12345
	ds_read_b128 v[124:127], v90 offset:0x2200
	v_add_f32_dpp v0, v0, v0 row_half_mirror row_mask:0xf bank_mask:0xf bound_ctrl:1
	s_mov_b32 s6, 0x12345
	ds_read2st64_b32 v[108:109], v89 offset0:208 offset1:209
	ds_read2st64_b64 v[100:103], v88 offset0:80 offset1:81
	v_add_f32_dpp v2, v0, v0 row_mirror row_mask:0xf bank_mask:0xf bound_ctrl:1
	v_add_f32_dpp v0, v0, v0 row_mirror row_mask:0xf bank_mask:0xf bound_ctrl:1
	s_mov_b32 s6, 0x12345
	s_waitcnt lgkmcnt(7)
	v_permlane16_swap_b32_e32 v0, v2
	v_add_f32_e64 v0, v0, v2
	v_pk_fma_f32 v[52:53], v[104:105], v[0:1], v[54:55] op_sel_hi:[1,0,1]
	v_pk_mul_f32 v[118:119], v[52:53], v[4:5] op_sel_hi:[0,1]
	v_pk_fma_f32 v[118:119], v[52:53], v[6:7], v[118:119] op_sel:[1,0,0]
	v_pk_mul_f32 v[10:11], v[110:111], v[10:11] op_sel:[1,0]
	v_pk_fma_f32 v[54:55], v[52:53], v[8:9], v[10:11]
	v_add_f32_dpp v118, v118, v118 quad_perm:[1,0,3,2] row_mask:0xf bank_mask:0xf bound_ctrl:1
	v_add_f32_dpp v119, v119, v119 quad_perm:[1,0,3,2] row_mask:0xf bank_mask:0xf bound_ctrl:1
	s_mov_b32 s6, 0x12345
	ds_read_b128 v[4:7], v90 offset:0x6400
	v_add_f32_dpp v118, v118, v118 quad_perm:[2,3,0,1] row_mask:0xf bank_mask:0xf bound_ctrl:1
	s_mov_b32 s6, 0x12345
	ds_read_b128 v[8:11], v90 offset:0x2400
	v_add_f32_dpp v118, v118, v118 row_half_mirror row_mask:0xf bank_mask:0xf bound_ctrl:1
	s_mov_b32 s6, 0x12345
	ds_write2_b32 v93, v1, v119 offset0:216 offset1:252
	v_add_f32_dpp v2, v118, v118 row_mirror row_mask:0xf bank_mask:0xf bound_ctrl:1
	v_add_f32_dpp v118, v118, v118 row_mirror row_mask:0xf bank_mask:0xf bound_ctrl:1
	s_mov_b32 s6, 0x12345
	s_waitcnt lgkmcnt(4)
	v_permlane16_swap_b32_e32 v118, v2
	v_add_f32_e64 v118, v118, v2
	v_pk_fma_f32 v[52:53], v[106:107], v[118:119], v[54:55] op_sel_hi:[1,0,1]
	s_cmp_eq_u32 s88, 0x800000
	s_cbranch_scc1 .LBB0_684
	s_nop 0
	v_pk_mul_f32 v[0:1], v[52:53], v[112:113] op_sel_hi:[0,1]
	v_pk_fma_f32 v[0:1], v[52:53], v[114:115], v[0:1] op_sel:[1,0,0]
	v_pk_mul_f32 v[98:99], v[108:109], v[98:99] op_sel_hi:[0,1]
	v_pk_fma_f32 v[54:55], v[52:53], v[96:97], v[98:99]
	v_add_f32_dpp v0, v0, v0 quad_perm:[1,0,3,2] row_mask:0xf bank_mask:0xf bound_ctrl:1
	v_add_f32_dpp v1, v1, v1 quad_perm:[1,0,3,2] row_mask:0xf bank_mask:0xf bound_ctrl:1
	s_mov_b32 s6, 0x12345
	ds_read_b128 v[112:115], v90 offset:0x6600
	v_add_f32_dpp v0, v0, v0 quad_perm:[2,3,0,1] row_mask:0xf bank_mask:0xf bound_ctrl:1
	s_mov_b32 s6, 0x12345
	ds_read_b128 v[96:99], v90 offset:0x2600
	v_add_f32_dpp v0, v0, v0 row_half_mirror row_mask:0xf bank_mask:0xf bound_ctrl:1
	s_mov_b32 s6, 0x12345
	ds_read2st64_b32 v[110:111], v89 offset0:210 offset1:211
	ds_read2st64_b64 v[104:107], v88 offset0:82 offset1:83
	v_add_f32_dpp v2, v0, v0 row_mirror row_mask:0xf bank_mask:0xf bound_ctrl:1
	v_add_f32_dpp v0, v0, v0 row_mirror row_mask:0xf bank_mask:0xf bound_ctrl:1
	v_add_u32_e32 v93, 0x480, v93
	s_waitcnt lgkmcnt(7)
	v_permlane16_swap_b32_e32 v0, v2
	v_add_f32_e64 v0, v0, v2
	v_pk_fma_f32 v[52:53], v[100:101], v[0:1], v[54:55] op_sel_hi:[1,0,1]
	v_pk_mul_f32 v[118:119], v[52:53], v[120:121] op_sel_hi:[0,1]
	v_pk_fma_f32 v[118:119], v[52:53], v[122:123], v[118:119] op_sel:[1,0,0]
	v_pk_mul_f32 v[126:127], v[108:109], v[126:127] op_sel:[1,0]
	v_pk_fma_f32 v[54:55], v[52:53], v[124:125], v[126:127]
	v_add_f32_dpp v118, v118, v118 quad_perm:[1,0,3,2] row_mask:0xf bank_mask:0xf bound_ctrl:1
	v_add_f32_dpp v119, v119, v119 quad_perm:[1,0,3,2] row_mask:0xf bank_mask:0xf bound_ctrl:1
	s_mov_b32 s6, 0x12345
	ds_read_b128 v[120:123], v90 offset:0x6800
	v_add_f32_dpp v118, v118, v118 quad_perm:[2,3,0,1] row_mask:0xf bank_mask:0xf bound_ctrl:1
	s_mov_b32 s6, 0x12345
	ds_read_b128 v[124:127], v90 offset:0x2800
	v_add_f32_dpp v118, v118, v118 row_half_mirror row_mask:0xf bank_mask:0xf bound_ctrl:1
	s_mov_b32 s6, 0x12345
	ds_write2_b32 v93, v1, v119 offset0:0 offset1:36
	v_add_f32_dpp v2, v118, v118 row_mirror row_mask:0xf bank_mask:0xf bound_ctrl:1
	v_add_f32_dpp v118, v118, v118 row_mirror row_mask:0xf bank_mask:0xf bound_ctrl:1
	s_mov_b32 s6, 0x12345
	s_waitcnt lgkmcnt(4)
	v_permlane16_swap_b32_e32 v118, v2
	v_add_f32_e64 v118, v118, v2
	v_pk_fma_f32 v[52:53], v[102:103], v[118:119], v[54:55] op_sel_hi:[1,0,1]
	v_pk_mul_f32 v[0:1], v[52:53], v[4:5] op_sel_hi:[0,1]
	v_pk_fma_f32 v[0:1], v[52:53], v[6:7], v[0:1] op_sel:[1,0,0]
	v_pk_mul_f32 v[10:11], v[110:111], v[10:11] op_sel_hi:[0,1]
	v_pk_fma_f32 v[54:55], v[52:53], v[8:9], v[10:11]
	v_add_f32_dpp v0, v0, v0 quad_perm:[1,0,3,2] row_mask:0xf bank_mask:0xf bound_ctrl:1
	v_add_f32_dpp v1, v1, v1 quad_perm:[1,0,3,2] row_mask:0xf bank_mask:0xf bound_ctrl:1
	s_mov_b32 s6, 0x12345
	ds_read_b128 v[4:7], v90 offset:0x6a00
	v_add_f32_dpp v0, v0, v0 quad_perm:[2,3,0,1] row_mask:0xf bank_mask:0xf bound_ctrl:1
	s_mov_b32 s6, 0x12345
	ds_read_b128 v[8:11], v90 offset:0x2a00
	v_add_f32_dpp v0, v0, v0 row_half_mirror row_mask:0xf bank_mask:0xf bound_ctrl:1
	s_mov_b32 s6, 0x12345
	ds_read2st64_b32 v[108:109], v89 offset0:212 offset1:213
	ds_read2st64_b64 v[100:103], v88 offset0:84 offset1:85
	v_add_f32_dpp v2, v0, v0 row_mirror row_mask:0xf bank_mask:0xf bound_ctrl:1
	v_add_f32_dpp v0, v0, v0 row_mirror row_mask:0xf bank_mask:0xf bound_ctrl:1
	s_mov_b32 s6, 0x12345
	s_waitcnt lgkmcnt(7)
	v_permlane16_swap_b32_e32 v0, v2
	v_add_f32_e64 v0, v0, v2
	v_pk_fma_f32 v[52:53], v[104:105], v[0:1], v[54:55] op_sel_hi:[1,0,1]
	v_pk_mul_f32 v[118:119], v[52:53], v[112:113] op_sel_hi:[0,1]
	v_pk_fma_f32 v[118:119], v[52:53], v[114:115], v[118:119] op_sel:[1,0,0]
	v_pk_mul_f32 v[98:99], v[110:111], v[98:99] op_sel:[1,0]
	v_pk_fma_f32 v[54:55], v[52:53], v[96:97], v[98:99]
	v_add_f32_dpp v118, v118, v118 quad_perm:[1,0,3,2] row_mask:0xf bank_mask:0xf bound_ctrl:1
	v_add_f32_dpp v119, v119, v119 quad_perm:[1,0,3,2] row_mask:0xf bank_mask:0xf bound_ctrl:1
	s_mov_b32 s6, 0x12345
	ds_read_b128 v[112:115], v90 offset:0x6c00
	v_add_f32_dpp v118, v118, v118 quad_perm:[2,3,0,1] row_mask:0xf bank_mask:0xf bound_ctrl:1
	s_mov_b32 s6, 0x12345
	ds_read_b128 v[96:99], v90 offset:0x2c00
	v_add_f32_dpp v118, v118, v118 row_half_mirror row_mask:0xf bank_mask:0xf bound_ctrl:1
	s_mov_b32 s6, 0x12345
	ds_write2_b32 v93, v1, v119 offset0:72 offset1:108
	v_add_f32_dpp v2, v118, v118 row_mirror row_mask:0xf bank_mask:0xf bound_ctrl:1
	v_add_f32_dpp v118, v118, v118 row_mirror row_mask:0xf bank_mask:0xf bound_ctrl:1
	s_mov_b32 s6, 0x12345
	s_waitcnt lgkmcnt(4)
	v_permlane16_swap_b32_e32 v118, v2
	v_add_f32_e64 v118, v118, v2
	v_pk_fma_f32 v[52:53], v[106:107], v[118:119], v[54:55] op_sel_hi:[1,0,1]
	v_pk_mul_f32 v[0:1], v[52:53], v[120:121] op_sel_hi:[0,1]
	v_pk_fma_f32 v[0:1], v[52:53], v[122:123], v[0:1] op_sel:[1,0,0]
	v_pk_mul_f32 v[126:127], v[108:109], v[126:127] op_sel_hi:[0,1]
	v_pk_fma_f32 v[54:55], v[52:53], v[124:125], v[126:127]
	v_add_f32_dpp v0, v0, v0 quad_perm:[1,0,3,2] row_mask:0xf bank_mask:0xf bound_ctrl:1
	v_add_f32_dpp v1, v1, v1 quad_perm:[1,0,3,2] row_mask:0xf bank_mask:0xf bound_ctrl:1
	s_mov_b32 s6, 0x12345
	ds_read_b128 v[120:123], v90 offset:0x6e00
	v_add_f32_dpp v0, v0, v0 quad_perm:[2,3,0,1] row_mask:0xf bank_mask:0xf bound_ctrl:1
	s_mov_b32 s6, 0x12345
	ds_read_b128 v[124:127], v90 offset:0x2e00
	v_add_f32_dpp v0, v0, v0 row_half_mirror row_mask:0xf bank_mask:0xf bound_ctrl:1
	s_mov_b32 s6, 0x12345
	ds_read2st64_b32 v[110:111], v89 offset0:214 offset1:215
	ds_read2st64_b64 v[104:107], v88 offset0:86 offset1:87
	v_add_f32_dpp v2, v0, v0 row_mirror row_mask:0xf bank_mask:0xf bound_ctrl:1
	v_add_f32_dpp v0, v0, v0 row_mirror row_mask:0xf bank_mask:0xf bound_ctrl:1
	s_mov_b32 s6, 0x12345
	s_waitcnt lgkmcnt(7)
	v_permlane16_swap_b32_e32 v0, v2
	v_add_f32_e64 v0, v0, v2
	v_pk_fma_f32 v[52:53], v[100:101], v[0:1], v[54:55] op_sel_hi:[1,0,1]
	v_pk_mul_f32 v[118:119], v[52:53], v[4:5] op_sel_hi:[0,1]
	v_pk_fma_f32 v[118:119], v[52:53], v[6:7], v[118:119] op_sel:[1,0,0]
	v_pk_mul_f32 v[10:11], v[108:109], v[10:11] op_sel:[1,0]
	v_pk_fma_f32 v[54:55], v[52:53], v[8:9], v[10:11]
	v_add_f32_dpp v118, v118, v118 quad_perm:[1,0,3,2] row_mask:0xf bank_mask:0xf bound_ctrl:1
	v_add_f32_dpp v119, v119, v119 quad_perm:[1,0,3,2] row_mask:0xf bank_mask:0xf bound_ctrl:1
	s_mov_b32 s6, 0x12345
	ds_read_b128 v[4:7], v90 offset:0x7000
	v_add_f32_dpp v118, v118, v118 quad_perm:[2,3,0,1] row_mask:0xf bank_mask:0xf bound_ctrl:1
	s_mov_b32 s6, 0x12345
	ds_read_b128 v[8:11], v90 offset:0x3000
	v_add_f32_dpp v118, v118, v118 row_half_mirror row_mask:0xf bank_mask:0xf bound_ctrl:1
	s_mov_b32 s6, 0x12345
	ds_write2_b32 v93, v1, v119 offset0:144 offset1:180
	v_add_f32_dpp v2, v118, v118 row_mirror row_mask:0xf bank_mask:0xf bound_ctrl:1
	v_add_f32_dpp v118, v118, v118 row_mirror row_mask:0xf bank_mask:0xf bound_ctrl:1
	s_mov_b32 s6, 0x12345
	s_waitcnt lgkmcnt(4)
	v_permlane16_swap_b32_e32 v118, v2
	v_add_f32_e64 v118, v118, v2
	v_pk_fma_f32 v[52:53], v[102:103], v[118:119], v[54:55] op_sel_hi:[1,0,1]
	v_pk_mul_f32 v[0:1], v[52:53], v[112:113] op_sel_hi:[0,1]
	v_pk_fma_f32 v[0:1], v[52:53], v[114:115], v[0:1] op_sel:[1,0,0]
	v_pk_mul_f32 v[98:99], v[110:111], v[98:99] op_sel_hi:[0,1]
	v_pk_fma_f32 v[54:55], v[52:53], v[96:97], v[98:99]
	v_add_f32_dpp v0, v0, v0 quad_perm:[1,0,3,2] row_mask:0xf bank_mask:0xf bound_ctrl:1
	v_add_f32_dpp v1, v1, v1 quad_perm:[1,0,3,2] row_mask:0xf bank_mask:0xf bound_ctrl:1
	s_mov_b32 s6, 0x12345
	ds_read_b128 v[112:115], v90 offset:0x7200
	v_add_f32_dpp v0, v0, v0 quad_perm:[2,3,0,1] row_mask:0xf bank_mask:0xf bound_ctrl:1
	s_mov_b32 s6, 0x12345
	ds_read_b128 v[96:99], v90 offset:0x3200
	v_add_f32_dpp v0, v0, v0 row_half_mirror row_mask:0xf bank_mask:0xf bound_ctrl:1
	s_mov_b32 s6, 0x12345
	ds_read2st64_b32 v[108:109], v89 offset0:216 offset1:217
	ds_read2st64_b64 v[100:103], v88 offset0:88 offset1:89
	v_add_f32_dpp v2, v0, v0 row_mirror row_mask:0xf bank_mask:0xf bound_ctrl:1
	v_add_f32_dpp v0, v0, v0 row_mirror row_mask:0xf bank_mask:0xf bound_ctrl:1
	s_mov_b32 s6, 0x12345
	s_waitcnt lgkmcnt(7)
	v_permlane16_swap_b32_e32 v0, v2
	v_add_f32_e64 v0, v0, v2
	v_pk_fma_f32 v[52:53], v[104:105], v[0:1], v[54:55] op_sel_hi:[1,0,1]
	v_pk_mul_f32 v[118:119], v[52:53], v[120:121] op_sel_hi:[0,1]
	v_pk_fma_f32 v[118:119], v[52:53], v[122:123], v[118:119] op_sel:[1,0,0]
	v_pk_mul_f32 v[126:127], v[110:111], v[126:127] op_sel:[1,0]
	v_pk_fma_f32 v[54:55], v[52:53], v[124:125], v[126:127]
	v_add_f32_dpp v118, v118, v118 quad_perm:[1,0,3,2] row_mask:0xf bank_mask:0xf bound_ctrl:1
	v_add_f32_dpp v119, v119, v119 quad_perm:[1,0,3,2] row_mask:0xf bank_mask:0xf bound_ctrl:1
	s_mov_b32 s6, 0x12345
	ds_read_b128 v[120:123], v90 offset:0x7400
	v_add_f32_dpp v118, v118, v118 quad_perm:[2,3,0,1] row_mask:0xf bank_mask:0xf bound_ctrl:1
	s_mov_b32 s6, 0x12345
	ds_read_b128 v[124:127], v90 offset:0x3400
	v_add_f32_dpp v118, v118, v118 row_half_mirror row_mask:0xf bank_mask:0xf bound_ctrl:1
	s_mov_b32 s6, 0x12345
	ds_write2_b32 v93, v1, v119 offset0:216 offset1:252
	v_add_f32_dpp v2, v118, v118 row_mirror row_mask:0xf bank_mask:0xf bound_ctrl:1
	v_add_f32_dpp v118, v118, v118 row_mirror row_mask:0xf bank_mask:0xf bound_ctrl:1
	s_mov_b32 s6, 0x12345
	s_waitcnt lgkmcnt(4)
	v_permlane16_swap_b32_e32 v118, v2
	v_add_f32_e64 v118, v118, v2
	v_pk_fma_f32 v[52:53], v[106:107], v[118:119], v[54:55] op_sel_hi:[1,0,1]
	v_pk_mul_f32 v[0:1], v[52:53], v[4:5] op_sel_hi:[0,1]
	v_pk_fma_f32 v[0:1], v[52:53], v[6:7], v[0:1] op_sel:[1,0,0]
	v_pk_mul_f32 v[10:11], v[108:109], v[10:11] op_sel_hi:[0,1]
	v_pk_fma_f32 v[54:55], v[52:53], v[8:9], v[10:11]
	v_add_f32_dpp v0, v0, v0 quad_perm:[1,0,3,2] row_mask:0xf bank_mask:0xf bound_ctrl:1
	v_add_f32_dpp v1, v1, v1 quad_perm:[1,0,3,2] row_mask:0xf bank_mask:0xf bound_ctrl:1
	s_mov_b32 s6, 0x12345
	ds_read_b128 v[4:7], v90 offset:0x7600
	v_add_f32_dpp v0, v0, v0 quad_perm:[2,3,0,1] row_mask:0xf bank_mask:0xf bound_ctrl:1
	s_mov_b32 s6, 0x12345
	ds_read_b128 v[8:11], v90 offset:0x3600
	v_add_f32_dpp v0, v0, v0 row_half_mirror row_mask:0xf bank_mask:0xf bound_ctrl:1
	s_mov_b32 s6, 0x12345
	ds_read2st64_b32 v[110:111], v89 offset0:218 offset1:219
	ds_read2st64_b64 v[104:107], v88 offset0:90 offset1:91
	v_add_f32_dpp v2, v0, v0 row_mirror row_mask:0xf bank_mask:0xf bound_ctrl:1
	v_add_f32_dpp v0, v0, v0 row_mirror row_mask:0xf bank_mask:0xf bound_ctrl:1
	v_add_u32_e32 v93, 0x480, v93
	s_waitcnt lgkmcnt(7)
	v_permlane16_swap_b32_e32 v0, v2
	v_add_f32_e64 v0, v0, v2
	v_pk_fma_f32 v[52:53], v[100:101], v[0:1], v[54:55] op_sel_hi:[1,0,1]
	v_pk_mul_f32 v[118:119], v[52:53], v[112:113] op_sel_hi:[0,1]
	v_pk_fma_f32 v[118:119], v[52:53], v[114:115], v[118:119] op_sel:[1,0,0]
	v_pk_mul_f32 v[98:99], v[108:109], v[98:99] op_sel:[1,0]
	v_pk_fma_f32 v[54:55], v[52:53], v[96:97], v[98:99]
	v_add_f32_dpp v118, v118, v118 quad_perm:[1,0,3,2] row_mask:0xf bank_mask:0xf bound_ctrl:1
	v_add_f32_dpp v119, v119, v119 quad_perm:[1,0,3,2] row_mask:0xf bank_mask:0xf bound_ctrl:1
	s_mov_b32 s6, 0x12345
	ds_read_b128 v[112:115], v90 offset:0x7800
	v_add_f32_dpp v118, v118, v118 quad_perm:[2,3,0,1] row_mask:0xf bank_mask:0xf bound_ctrl:1
	s_mov_b32 s6, 0x12345
	ds_read_b128 v[96:99], v90 offset:0x3800
	v_add_f32_dpp v118, v118, v118 row_half_mirror row_mask:0xf bank_mask:0xf bound_ctrl:1
	s_mov_b32 s6, 0x12345
	ds_write2_b32 v93, v1, v119 offset0:0 offset1:36
	v_add_f32_dpp v2, v118, v118 row_mirror row_mask:0xf bank_mask:0xf bound_ctrl:1
	v_add_f32_dpp v118, v118, v118 row_mirror row_mask:0xf bank_mask:0xf bound_ctrl:1
	s_mov_b32 s6, 0x12345
	s_waitcnt lgkmcnt(4)
	v_permlane16_swap_b32_e32 v118, v2
	v_add_f32_e64 v118, v118, v2
	v_pk_fma_f32 v[52:53], v[102:103], v[118:119], v[54:55] op_sel_hi:[1,0,1]
	v_pk_mul_f32 v[0:1], v[52:53], v[120:121] op_sel_hi:[0,1]
	v_pk_fma_f32 v[0:1], v[52:53], v[122:123], v[0:1] op_sel:[1,0,0]
	v_pk_mul_f32 v[126:127], v[110:111], v[126:127] op_sel_hi:[0,1]
	v_pk_fma_f32 v[54:55], v[52:53], v[124:125], v[126:127]
	v_add_f32_dpp v0, v0, v0 quad_perm:[1,0,3,2] row_mask:0xf bank_mask:0xf bound_ctrl:1
	v_add_f32_dpp v1, v1, v1 quad_perm:[1,0,3,2] row_mask:0xf bank_mask:0xf bound_ctrl:1
	s_mov_b32 s6, 0x12345
	ds_read_b128 v[120:123], v90 offset:0x7a00
	v_add_f32_dpp v0, v0, v0 quad_perm:[2,3,0,1] row_mask:0xf bank_mask:0xf bound_ctrl:1
	s_mov_b32 s6, 0x12345
	ds_read_b128 v[124:127], v90 offset:0x3a00
	v_add_f32_dpp v0, v0, v0 row_half_mirror row_mask:0xf bank_mask:0xf bound_ctrl:1
	s_mov_b32 s6, 0x12345
	ds_read2st64_b32 v[108:109], v89 offset0:220 offset1:221
	ds_read2st64_b64 v[100:103], v88 offset0:92 offset1:93
	v_add_f32_dpp v2, v0, v0 row_mirror row_mask:0xf bank_mask:0xf bound_ctrl:1
	v_add_f32_dpp v0, v0, v0 row_mirror row_mask:0xf bank_mask:0xf bound_ctrl:1
	s_mov_b32 s6, 0x12345
	s_waitcnt lgkmcnt(7)
	v_permlane16_swap_b32_e32 v0, v2
	v_add_f32_e64 v0, v0, v2
	v_pk_fma_f32 v[52:53], v[104:105], v[0:1], v[54:55] op_sel_hi:[1,0,1]
	v_pk_mul_f32 v[118:119], v[52:53], v[4:5] op_sel_hi:[0,1]
	v_pk_fma_f32 v[118:119], v[52:53], v[6:7], v[118:119] op_sel:[1,0,0]
	v_pk_mul_f32 v[10:11], v[110:111], v[10:11] op_sel:[1,0]
	v_pk_fma_f32 v[54:55], v[52:53], v[8:9], v[10:11]
	v_add_f32_dpp v118, v118, v118 quad_perm:[1,0,3,2] row_mask:0xf bank_mask:0xf bound_ctrl:1
	v_add_f32_dpp v119, v119, v119 quad_perm:[1,0,3,2] row_mask:0xf bank_mask:0xf bound_ctrl:1
	s_mov_b32 s6, 0x12345
	ds_read_b128 v[4:7], v90 offset:0x7c00
	v_add_f32_dpp v118, v118, v118 quad_perm:[2,3,0,1] row_mask:0xf bank_mask:0xf bound_ctrl:1
	s_mov_b32 s6, 0x12345
	ds_read_b128 v[8:11], v90 offset:0x3c00
	v_add_f32_dpp v118, v118, v118 row_half_mirror row_mask:0xf bank_mask:0xf bound_ctrl:1
	s_mov_b32 s6, 0x12345
	ds_write2_b32 v93, v1, v119 offset0:72 offset1:108
	v_add_f32_dpp v2, v118, v118 row_mirror row_mask:0xf bank_mask:0xf bound_ctrl:1
	v_add_f32_dpp v118, v118, v118 row_mirror row_mask:0xf bank_mask:0xf bound_ctrl:1
	s_mov_b32 s6, 0x12345
	s_waitcnt lgkmcnt(4)
	v_permlane16_swap_b32_e32 v118, v2
	v_add_f32_e64 v118, v118, v2
	v_pk_fma_f32 v[52:53], v[106:107], v[118:119], v[54:55] op_sel_hi:[1,0,1]
	v_pk_mul_f32 v[0:1], v[52:53], v[112:113] op_sel_hi:[0,1]
	v_pk_fma_f32 v[0:1], v[52:53], v[114:115], v[0:1] op_sel:[1,0,0]
	v_pk_mul_f32 v[98:99], v[108:109], v[98:99] op_sel_hi:[0,1]
	v_pk_fma_f32 v[54:55], v[52:53], v[96:97], v[98:99]
	v_add_f32_dpp v0, v0, v0 quad_perm:[1,0,3,2] row_mask:0xf bank_mask:0xf bound_ctrl:1
	v_add_f32_dpp v1, v1, v1 quad_perm:[1,0,3,2] row_mask:0xf bank_mask:0xf bound_ctrl:1
	s_mov_b32 s6, 0x12345
	ds_read_b128 v[112:115], v90 offset:0x7e00
	v_add_f32_dpp v0, v0, v0 quad_perm:[2,3,0,1] row_mask:0xf bank_mask:0xf bound_ctrl:1
	s_mov_b32 s6, 0x12345
	ds_read_b128 v[96:99], v90 offset:0x3e00
	v_add_f32_dpp v0, v0, v0 row_half_mirror row_mask:0xf bank_mask:0xf bound_ctrl:1
	s_mov_b32 s6, 0x12345
	ds_read2st64_b32 v[110:111], v89 offset0:222 offset1:223
	ds_read2st64_b64 v[104:107], v88 offset0:94 offset1:95
	v_add_f32_dpp v2, v0, v0 row_mirror row_mask:0xf bank_mask:0xf bound_ctrl:1
	v_add_f32_dpp v0, v0, v0 row_mirror row_mask:0xf bank_mask:0xf bound_ctrl:1
	s_mov_b32 s6, 0x12345
	s_waitcnt lgkmcnt(7)
	v_permlane16_swap_b32_e32 v0, v2
	v_add_f32_e64 v0, v0, v2
	v_pk_fma_f32 v[52:53], v[100:101], v[0:1], v[54:55] op_sel_hi:[1,0,1]
	v_pk_mul_f32 v[118:119], v[52:53], v[120:121] op_sel_hi:[0,1]
	v_pk_fma_f32 v[118:119], v[52:53], v[122:123], v[118:119] op_sel:[1,0,0]
	v_pk_mul_f32 v[126:127], v[108:109], v[126:127] op_sel:[1,0]
	v_pk_fma_f32 v[54:55], v[52:53], v[124:125], v[126:127]
	v_add_f32_dpp v118, v118, v118 quad_perm:[1,0,3,2] row_mask:0xf bank_mask:0xf bound_ctrl:1
	v_add_f32_dpp v119, v119, v119 quad_perm:[1,0,3,2] row_mask:0xf bank_mask:0xf bound_ctrl:1
	s_mov_b32 s6, 0x12345
	s_mov_b32 s6, 0x12345
	v_add_f32_dpp v118, v118, v118 quad_perm:[2,3,0,1] row_mask:0xf bank_mask:0xf bound_ctrl:1
	s_mov_b32 s6, 0x12345
	s_mov_b32 s6, 0x12345
	v_add_f32_dpp v118, v118, v118 row_half_mirror row_mask:0xf bank_mask:0xf bound_ctrl:1
	s_mov_b32 s6, 0x12345
	ds_write2_b32 v93, v1, v119 offset0:144 offset1:180
	v_add_f32_dpp v2, v118, v118 row_mirror row_mask:0xf bank_mask:0xf bound_ctrl:1
	v_add_f32_dpp v118, v118, v118 row_mirror row_mask:0xf bank_mask:0xf bound_ctrl:1
	s_mov_b32 s6, 0x12345
	s_waitcnt lgkmcnt(2)
	v_permlane16_swap_b32_e32 v118, v2
	v_add_f32_e64 v118, v118, v2
	v_pk_fma_f32 v[52:53], v[102:103], v[118:119], v[54:55] op_sel_hi:[1,0,1]
	v_pk_mul_f32 v[0:1], v[52:53], v[4:5] op_sel_hi:[0,1]
	v_pk_fma_f32 v[0:1], v[52:53], v[6:7], v[0:1] op_sel:[1,0,0]
	v_pk_mul_f32 v[10:11], v[110:111], v[10:11] op_sel_hi:[0,1]
	v_pk_fma_f32 v[54:55], v[52:53], v[8:9], v[10:11]
	v_add_f32_dpp v0, v0, v0 quad_perm:[1,0,3,2] row_mask:0xf bank_mask:0xf bound_ctrl:1
	v_add_f32_dpp v1, v1, v1 quad_perm:[1,0,3,2] row_mask:0xf bank_mask:0xf bound_ctrl:1
	s_mov_b32 s6, 0x12345
	s_mov_b32 s6, 0x12345
	v_add_f32_dpp v0, v0, v0 quad_perm:[2,3,0,1] row_mask:0xf bank_mask:0xf bound_ctrl:1
	s_mov_b32 s6, 0x12345
	s_mov_b32 s6, 0x12345
	v_add_f32_dpp v0, v0, v0 row_half_mirror row_mask:0xf bank_mask:0xf bound_ctrl:1
	s_mov_b32 s6, 0x12345
	s_mov_b32 s6, 0x12345
	v_add_f32_dpp v2, v0, v0 row_mirror row_mask:0xf bank_mask:0xf bound_ctrl:1
	v_add_f32_dpp v0, v0, v0 row_mirror row_mask:0xf bank_mask:0xf bound_ctrl:1
	s_mov_b32 s6, 0x12345
	s_waitcnt lgkmcnt(1)
	v_permlane16_swap_b32_e32 v0, v2
	v_add_f32_e64 v0, v0, v2
	v_pk_fma_f32 v[52:53], v[104:105], v[0:1], v[54:55] op_sel_hi:[1,0,1]
	v_pk_mul_f32 v[118:119], v[52:53], v[112:113] op_sel_hi:[0,1]
	v_pk_fma_f32 v[118:119], v[52:53], v[114:115], v[118:119] op_sel:[1,0,0]
	v_pk_mul_f32 v[98:99], v[110:111], v[98:99] op_sel:[1,0]
	v_pk_fma_f32 v[54:55], v[52:53], v[96:97], v[98:99]
	v_add_f32_dpp v118, v118, v118 quad_perm:[1,0,3,2] row_mask:0xf bank_mask:0xf bound_ctrl:1
	v_add_f32_dpp v119, v119, v119 quad_perm:[1,0,3,2] row_mask:0xf bank_mask:0xf bound_ctrl:1
	s_mov_b32 s6, 0x12345
	s_mov_b32 s6, 0x12345
	v_add_f32_dpp v118, v118, v118 quad_perm:[2,3,0,1] row_mask:0xf bank_mask:0xf bound_ctrl:1
	s_mov_b32 s6, 0x12345
	s_mov_b32 s6, 0x12345
	v_add_f32_dpp v118, v118, v118 row_half_mirror row_mask:0xf bank_mask:0xf bound_ctrl:1
	s_mov_b32 s6, 0x12345
	ds_write2_b32 v93, v1, v119 offset0:216 offset1:252
	v_add_f32_dpp v2, v118, v118 row_mirror row_mask:0xf bank_mask:0xf bound_ctrl:1
	v_add_f32_dpp v118, v118, v118 row_mirror row_mask:0xf bank_mask:0xf bound_ctrl:1
	s_mov_b32 s6, 0x12345
	s_nop 0
	v_permlane16_swap_b32_e32 v118, v2
	v_add_f32_e64 v118, v118, v2
	v_pk_fma_f32 v[52:53], v[106:107], v[118:119], v[54:55] op_sel_hi:[1,0,1]
